# in-proj / out-proj K loops: second-k-step fragment reads issued two per gap behind the first three MFMAs so five MFMAs cover them before the pre-barrier lgkmcnt(0)
# baseline (speedup 1.0000x reference)
; DI int otid() { int t = threadIdx.x; asm volatile("" : "+v"(t)); return t; }
; #define G_ISSUE(ks_, buf_) do { \
;     const bf16_t* wq_ = wp + (ks_) * wks; const bf16_t* xq_ = xp + (ks_) * xks; char* lb_ = ld + (buf_) * STAGE; \
;     dma16(wq_, lb_); dma16(wq_ + 2048, lb_ + 4096); \
;     _Pragma("unroll") for (int i_ = 0; i_ < TJ; ++i_) dma16(xq_ + i_ * 2048, lb_ + 8192 + i_ * 4096); } while (0)
; template <bool VMODE, int TJ>
; DI void gemm_mainloop(const bf16_t* __restrict__ W, const bf16_t* __restrict__ X, int NW, char* smem, f32x16 (&acc)[2][TJ]) {
;     constexpr int XROWS = 64 * TJ, STAGE = (128 + XROWS) * 64, NPW = 2 + TJ;
;     const int tid = otid(), lane = tid & 63, wave = tid >> 6, r = lane & 31, h = lane >> 5, wf = wave & 1, wt = wave >> 1;
;     const int goff = (16 * wave + (lane >> 2)) * 32 + (((lane & 3) ^ (lane >> 4)) << 3);
;     const bf16_t* wp = W + goff;
;     const bf16_t* xp = X + goff;
;     const size_t wks = (size_t)NW * 32, xks = (size_t)NTOK * 32;
;     char* ld = smem + tid * 16;
;     ...
;     const int xr = (r >> 2) & 3;
;     const int fo0 = r * 64 + (((0 + h) ^ xr) << 4), fo1 = r * 64 + (((2 + h) ^ xr) << 4);
;     __syncthreads();
;     ...
;         G_ISSUE(0, 0);
;         G_ISSUE(1, 1);
;         int bc = 0, bn = 2;
;         for (int ks = 0; ks < 32; ++ks) {
;             if (ks < 31) asm volatile("s_waitcnt vmcnt(6)" ::: "memory");
;             else asm volatile("s_waitcnt vmcnt(0)" ::: "memory");
;             __builtin_amdgcn_s_barrier();
.LBB0_39:
	v_mov_b32_e32 v116, v200
	s_cmp_lg_u32 s6, 0
	s_cbranch_scc1 .Lop4_second
	s_load_dwordx2 s[8:9], s[0:1], 0xd8
	s_load_dwordx2 s[56:57], s[0:1], 0xb8
	s_mov_b64 s[62:63], 0
	v_readlane_b32 s4, v254, 13
	s_nop 0
	s_add_i32 s4, s6, s4
	s_and_b32 s28, s4, 0x7fffff80
	s_waitcnt lgkmcnt(0)
	s_add_u32 s8, s8, s58
	s_addc_u32 s9, s9, s59
	v_readlane_b32 s4, v254, 14
	s_nop 0
	s_add_u32 s4, s8, s4
	s_addc_u32 s5, s9, 0
	v_readlane_b32 s6, v255, 23
	s_nop 0
	s_add_i32 s6, s6, s28
	s_mov_b32 s7, s75
	s_lshl_b64 s[6:7], s[6:7], 6
	s_add_u32 s6, s56, s6
	s_addc_u32 s7, s57, s7
	v_bfe_u32 v1, v200, 4, 2
	v_bitop3_b32 v1, v1, v200, 3 bitop3:0x78
	v_lshlrev_b32_e32 v0, 3, v200
	v_lshlrev_b32_e32 v1, 3, v1
	s_movk_i32 s29, 0xffe0
	v_and_or_b32 v0, v0, s29, v1
	v_lshlrev_b32_e32 v128, 1, v0
	v_lshl_add_u32 v130, v200, 4, 32
	v_bfe_u32 v5, v200, 5, 1
	v_bfe_u32 v7, v200, 2, 2
	v_bitop3_b32 v9, v5, v7, 2 bitop3:0x36
	v_lshrrev_b32_e32 v6, 2, v200
	v_lshlrev_b32_e32 v8, 6, v200
	v_bitop3_b32 v6, v5, v6, 3 bitop3:0x78
	v_and_b32_e32 v10, 0x7c0, v8
	v_lshl_or_b32 v131, v6, 4, v10
	v_lshl_or_b32 v132, v9, 4, v10
	v_and_b32_e32 v134, 0x1000, v8
	v_and_b32_e32 v133, 0xffffe000, v8
	v_mov_b32_e32 v170, v128
	v_add_u32_e32 v171, 0x1000, v128
	v_add_u32_e32 v172, 0x10000, v128
	v_add_u32_e32 v173, 0x11000, v128
	v_readfirstlane_b32 s100, v130
	v_mov_b32_e32 v0, 0
	v_mov_b32_e32 v1, 0
	v_mov_b32_e32 v2, 0
	v_mov_b32_e32 v3, 0
	v_mov_b32_e32 v4, 0
	v_mov_b32_e32 v5, 0
	v_mov_b32_e32 v6, 0
	v_mov_b32_e32 v7, 0
	v_mov_b32_e32 v8, 0
	v_mov_b32_e32 v9, 0
	v_mov_b32_e32 v10, 0
	v_mov_b32_e32 v11, 0
	v_mov_b32_e32 v12, 0
	v_mov_b32_e32 v13, 0
	v_mov_b32_e32 v14, 0
	v_mov_b32_e32 v15, 0
	v_mov_b32_e32 v16, 0
	v_mov_b32_e32 v17, 0
	v_mov_b32_e32 v18, 0
	v_mov_b32_e32 v19, 0
	v_mov_b32_e32 v20, 0
	v_mov_b32_e32 v21, 0
	v_mov_b32_e32 v22, 0
	v_mov_b32_e32 v23, 0
	v_mov_b32_e32 v24, 0
	v_mov_b32_e32 v25, 0
	v_mov_b32_e32 v26, 0
	v_mov_b32_e32 v27, 0
	v_mov_b32_e32 v28, 0
	v_mov_b32_e32 v29, 0
	v_mov_b32_e32 v30, 0
	v_mov_b32_e32 v31, 0
	v_mov_b32_e32 v32, 0
	v_mov_b32_e32 v33, 0
	v_mov_b32_e32 v34, 0
	v_mov_b32_e32 v35, 0
	v_mov_b32_e32 v36, 0
	v_mov_b32_e32 v37, 0
	v_mov_b32_e32 v38, 0
	v_mov_b32_e32 v39, 0
	v_mov_b32_e32 v40, 0
	v_mov_b32_e32 v41, 0
	v_mov_b32_e32 v42, 0
	v_mov_b32_e32 v43, 0
	v_mov_b32_e32 v44, 0
	v_mov_b32_e32 v45, 0
	v_mov_b32_e32 v46, 0
	v_mov_b32_e32 v47, 0
	v_mov_b32_e32 v48, 0
	v_mov_b32_e32 v49, 0
	v_mov_b32_e32 v50, 0
	v_mov_b32_e32 v51, 0
	v_mov_b32_e32 v52, 0
	v_mov_b32_e32 v53, 0
	v_mov_b32_e32 v54, 0
	v_mov_b32_e32 v55, 0
	v_mov_b32_e32 v56, 0
	v_mov_b32_e32 v57, 0
	v_mov_b32_e32 v58, 0
	v_mov_b32_e32 v59, 0
	v_mov_b32_e32 v60, 0
	v_mov_b32_e32 v61, 0
	v_mov_b32_e32 v62, 0
	v_mov_b32_e32 v63, 0
	v_mov_b32_e32 v64, 0
	v_mov_b32_e32 v65, 0
	v_mov_b32_e32 v66, 0
	v_mov_b32_e32 v67, 0
	v_mov_b32_e32 v68, 0
	v_mov_b32_e32 v69, 0
	v_mov_b32_e32 v70, 0
	v_mov_b32_e32 v71, 0
	v_mov_b32_e32 v72, 0
	v_mov_b32_e32 v73, 0
	v_mov_b32_e32 v74, 0
	v_mov_b32_e32 v75, 0
	v_mov_b32_e32 v76, 0
	v_mov_b32_e32 v77, 0
	v_mov_b32_e32 v78, 0
	v_mov_b32_e32 v79, 0
	v_mov_b32_e32 v80, 0
	v_mov_b32_e32 v81, 0
	v_mov_b32_e32 v82, 0
	v_mov_b32_e32 v83, 0
	v_mov_b32_e32 v84, 0
	v_mov_b32_e32 v85, 0
	v_mov_b32_e32 v86, 0
	v_mov_b32_e32 v87, 0
	v_mov_b32_e32 v88, 0
	v_mov_b32_e32 v89, 0
	v_mov_b32_e32 v90, 0
	v_mov_b32_e32 v91, 0
	v_mov_b32_e32 v92, 0
	v_mov_b32_e32 v93, 0
	v_mov_b32_e32 v94, 0
	v_mov_b32_e32 v95, 0
	v_mov_b32_e32 v96, 0
	v_mov_b32_e32 v97, 0
	v_mov_b32_e32 v98, 0
	v_mov_b32_e32 v99, 0
	v_mov_b32_e32 v100, 0
	v_mov_b32_e32 v101, 0
	v_mov_b32_e32 v102, 0
	v_mov_b32_e32 v103, 0
	v_mov_b32_e32 v104, 0
	v_mov_b32_e32 v105, 0
	v_mov_b32_e32 v106, 0
	v_mov_b32_e32 v107, 0
	v_mov_b32_e32 v108, 0
	v_mov_b32_e32 v109, 0
	v_mov_b32_e32 v110, 0
	v_mov_b32_e32 v111, 0
	v_mov_b32_e32 v112, 0
	v_mov_b32_e32 v113, 0
	v_mov_b32_e32 v114, 0
	v_mov_b32_e32 v115, 0
	v_mov_b32_e32 v116, 0
	v_mov_b32_e32 v117, 0
	v_mov_b32_e32 v118, 0
	v_mov_b32_e32 v119, 0
	v_mov_b32_e32 v120, 0
	v_mov_b32_e32 v121, 0
	v_mov_b32_e32 v122, 0
	v_mov_b32_e32 v123, 0
	v_mov_b32_e32 v124, 0
	v_mov_b32_e32 v125, 0
	v_mov_b32_e32 v126, 0
	v_mov_b32_e32 v127, 0
	s_barrier
	s_mov_b32 s101, s100
	s_mov_b32 m0, s101
	s_nop 0
	global_load_lds_dwordx4 v170, s[4:5]
	s_add_u32 m0, s101, 0x1000
	s_nop 0
	global_load_lds_dwordx4 v171, s[4:5]
	s_add_u32 m0, s101, 0x2000
	s_nop 0
	global_load_lds_dwordx4 v172, s[6:7]
	s_add_u32 m0, s101, 0x3000
	s_nop 0
	global_load_lds_dwordx4 v170, s[6:7]
	s_add_u32 m0, s101, 0x4000
	s_nop 0
	global_load_lds_dwordx4 v173, s[6:7]
	s_add_u32 m0, s101, 0x5000
	s_nop 0
	global_load_lds_dwordx4 v171, s[6:7]
	s_add_u32 s4, s4, 0x10000
	s_addc_u32 s5, s5, 0
	s_add_u32 s6, s6, 0x120000
	s_addc_u32 s7, s7, 0
	s_add_i32 s101, s100, 0x6000
	s_mov_b32 m0, s101
	s_nop 0
	global_load_lds_dwordx4 v170, s[4:5]
	s_add_u32 m0, s101, 0x1000
	s_nop 0
	global_load_lds_dwordx4 v171, s[4:5]
	s_add_u32 m0, s101, 0x2000
	s_nop 0
	global_load_lds_dwordx4 v172, s[6:7]
	s_add_u32 m0, s101, 0x3000
	s_nop 0
	global_load_lds_dwordx4 v170, s[6:7]
	s_add_u32 m0, s101, 0x4000
	s_nop 0
	global_load_lds_dwordx4 v173, s[6:7]
	s_add_u32 m0, s101, 0x5000
	s_nop 0
	global_load_lds_dwordx4 v171, s[6:7]
	s_add_u32 s4, s4, 0x10000
	s_addc_u32 s5, s5, 0
	s_add_u32 s6, s6, 0x120000
	s_addc_u32 s7, s7, 0
	s_mov_b32 s34, 0
	s_mov_b32 s35, 2
	s_mov_b32 s29, 29
	s_mul_i32 s40, s34, 0x6000
	s_add_i32 s40, s40, 32
	v_add_u32_e32 v135, s40, v134
	v_add_u32_e32 v168, s40, v133
	v_add_u32_e32 v194, v135, v131
	v_add_u32_e32 v195, v168, v131
	s_waitcnt vmcnt(6)
	s_waitcnt lgkmcnt(0)
	s_barrier
; #define MFMA(a, b, c) __builtin_amdgcn_mfma_f32_32x32x16_bf16((a), (b), (c), 0, 0, 0)
; #define G_ISSUE(ks_, buf_) do { \
;     const bf16_t* wq_ = wp + (ks_) * wks; const bf16_t* xq_ = xp + (ks_) * xks; char* lb_ = ld + (buf_) * STAGE; \
;     dma16(wq_, lb_); dma16(wq_ + 2048, lb_ + 4096); \
;     _Pragma("unroll") for (int i_ = 0; i_ < TJ; ++i_) dma16(xq_ + i_ * 2048, lb_ + 8192 + i_ * 4096); } while (0)
; template <bool VMODE, int TJ>
; DI void gemm_mainloop(const bf16_t* __restrict__ W, const bf16_t* __restrict__ X, int NW, char* smem, f32x16 (&acc)[2][TJ]) {
;     ...
;         for (int ks = 0; ks < 32; ++ks) {
;             if (ks < 31) asm volatile("s_waitcnt vmcnt(6)" ::: "memory");
;             else asm volatile("s_waitcnt vmcnt(0)" ::: "memory");
;             __builtin_amdgcn_s_barrier();
;             const char* sw = smem + bc * STAGE + wf * 64 * 64;
;             const char* sx = smem + bc * STAGE + 8192 + wt * (32 * TJ) * 64;
;             bf16x8 fw[2], fx[TJ], gw[2], gx[TJ];
; #pragma unroll
;             for (int i = 0; i < 2; ++i) fw[i] = *(const bf16x8*)(sw + i * 32 * 64 + fo0);
; #pragma unroll
;             for (int j = 0; j < TJ; ++j) fx[j] = *(const bf16x8*)(sx + j * 32 * 64 + fo0);
;             __builtin_amdgcn_sched_barrier(0);
;             if (ks + 2 < 32) G_ISSUE(ks + 2, bn);
;             __builtin_amdgcn_sched_barrier(0);
; #pragma unroll
;             for (int i = 0; i < 2; ++i) gw[i] = *(const bf16x8*)(sw + i * 32 * 64 + fo1);
; #pragma unroll
;             for (int j = 0; j < TJ; ++j) gx[j] = *(const bf16x8*)(sx + j * 32 * 64 + fo1);
; #pragma unroll
;             for (int i = 0; i < 2; ++i)
; #pragma unroll
;                 for (int j = 0; j < TJ; ++j) acc[i][j] = VMODE ? MFMA(fx[j], fw[i], acc[i][j]) : MFMA(fw[i], fx[j], acc[i][j]);
; #pragma unroll
;             for (int i = 0; i < 2; ++i)
; #pragma unroll
;                 for (int j = 0; j < TJ; ++j) acc[i][j] = VMODE ? MFMA(gx[j], gw[i], acc[i][j]) : MFMA(gw[i], gx[j], acc[i][j]);
;             bc = (bc == 2) ? 0 : bc + 1; bn = (bn == 2) ? 0 : bn + 1;
	ds_read_b128 v[136:139], v194
	ds_read_b128 v[140:143], v194 offset:2048
	ds_read_b128 v[144:147], v195 offset:8192
	ds_read_b128 v[148:151], v195 offset:10240
	ds_read_b128 v[152:155], v195 offset:12288
	ds_read_b128 v[156:159], v195 offset:14336
	s_mul_i32 s40, s35, 0x6000
	s_add_i32 s101, s40, s100
	s_add_i32 s40, s34, 1
	s_cmp_lg_u32 s34, 2
	s_cselect_b32 s34, s40, 0
	s_add_i32 s40, s35, 1
	s_cmp_lg_u32 s35, 2
	s_cselect_b32 s35, s40, 0
	v_add_u32_e32 v169, v135, v132
	v_add_u32_e32 v196, v168, v132
	s_mov_b32 m0, s101
	s_nop 0
	global_load_lds_dwordx4 v170, s[4:5]
	s_add_u32 m0, s101, 0x1000
	s_nop 0
	global_load_lds_dwordx4 v171, s[4:5]
	s_add_u32 m0, s101, 0x2000
	s_nop 0
	global_load_lds_dwordx4 v172, s[6:7]
	s_add_u32 m0, s101, 0x3000
	s_nop 0
	global_load_lds_dwordx4 v170, s[6:7]
	s_add_u32 m0, s101, 0x4000
	s_nop 0
	global_load_lds_dwordx4 v173, s[6:7]
	s_add_u32 m0, s101, 0x5000
	s_nop 0
	global_load_lds_dwordx4 v171, s[6:7]
	s_add_u32 s4, s4, 0x10000
	s_addc_u32 s5, s5, 0
	s_add_u32 s6, s6, 0x120000
	s_addc_u32 s7, s7, 0
	s_waitcnt lgkmcnt(0)
	v_mfma_f32_32x32x16_bf16 v[112:127], v[136:139], v[144:147], v[112:127]
	ds_read_b128 v[160:163], v169
	ds_read_b128 v[176:179], v169 offset:2048
	v_mfma_f32_32x32x16_bf16 v[96:111], v[136:139], v[148:151], v[96:111]
	ds_read_b128 v[164:167], v196 offset:8192
	ds_read_b128 v[180:183], v196 offset:10240
	v_mfma_f32_32x32x16_bf16 v[48:63], v[136:139], v[152:155], v[48:63]
	ds_read_b128 v[184:187], v196 offset:12288
	ds_read_b128 v[188:191], v196 offset:14336
	v_mfma_f32_32x32x16_bf16 v[32:47], v[136:139], v[156:159], v[32:47]
	v_mfma_f32_32x32x16_bf16 v[80:95], v[140:143], v[144:147], v[80:95]
	v_mfma_f32_32x32x16_bf16 v[64:79], v[140:143], v[148:151], v[64:79]
	v_mfma_f32_32x32x16_bf16 v[16:31], v[140:143], v[152:155], v[16:31]
	v_mfma_f32_32x32x16_bf16 v[0:15], v[140:143], v[156:159], v[0:15]
.Lop4_loop:
	s_mul_i32 s40, s34, 0x6000
	s_add_i32 s40, s40, 32
	v_add_u32_e32 v135, s40, v134
	v_add_u32_e32 v168, s40, v133
	v_add_u32_e32 v194, v135, v131
	v_add_u32_e32 v195, v168, v131
	s_waitcnt vmcnt(6)
	s_waitcnt lgkmcnt(0)
	s_barrier
	ds_read_b128 v[136:139], v194
	ds_read_b128 v[140:143], v194 offset:2048
	ds_read_b128 v[144:147], v195 offset:8192
	ds_read_b128 v[148:151], v195 offset:10240
	ds_read_b128 v[152:155], v195 offset:12288
	ds_read_b128 v[156:159], v195 offset:14336
	s_mul_i32 s40, s35, 0x6000
	s_add_i32 s101, s40, s100
	s_add_i32 s40, s34, 1
	s_cmp_lg_u32 s34, 2
	s_cselect_b32 s34, s40, 0
	s_add_i32 s40, s35, 1
	s_cmp_lg_u32 s35, 2
	s_cselect_b32 s35, s40, 0
	v_add_u32_e32 v169, v135, v132
	v_add_u32_e32 v196, v168, v132
	s_mov_b32 m0, s101
	v_mfma_f32_32x32x16_bf16 v[112:127], v[160:163], v[164:167], v[112:127]
	global_load_lds_dwordx4 v170, s[4:5]
	s_add_u32 m0, s101, 0x1000
	v_mfma_f32_32x32x16_bf16 v[96:111], v[160:163], v[180:183], v[96:111]
	global_load_lds_dwordx4 v171, s[4:5]
	s_add_u32 m0, s101, 0x2000
	v_mfma_f32_32x32x16_bf16 v[48:63], v[160:163], v[184:187], v[48:63]
	global_load_lds_dwordx4 v172, s[6:7]
	s_add_u32 m0, s101, 0x3000
	v_mfma_f32_32x32x16_bf16 v[32:47], v[160:163], v[188:191], v[32:47]
	global_load_lds_dwordx4 v170, s[6:7]
	s_add_u32 m0, s101, 0x4000
	v_mfma_f32_32x32x16_bf16 v[80:95], v[176:179], v[164:167], v[80:95]
	global_load_lds_dwordx4 v173, s[6:7]
	s_add_u32 m0, s101, 0x5000
	v_mfma_f32_32x32x16_bf16 v[64:79], v[176:179], v[180:183], v[64:79]
	global_load_lds_dwordx4 v171, s[6:7]
	s_add_u32 s4, s4, 0x10000
	s_addc_u32 s5, s5, 0
	s_add_u32 s6, s6, 0x120000
	s_addc_u32 s7, s7, 0
	v_mfma_f32_32x32x16_bf16 v[16:31], v[176:179], v[184:187], v[16:31]
	v_mfma_f32_32x32x16_bf16 v[0:15], v[176:179], v[188:191], v[0:15]
	s_waitcnt lgkmcnt(0)
	v_mfma_f32_32x32x16_bf16 v[112:127], v[136:139], v[144:147], v[112:127]
	ds_read_b128 v[160:163], v169
	ds_read_b128 v[176:179], v169 offset:2048
	v_mfma_f32_32x32x16_bf16 v[96:111], v[136:139], v[148:151], v[96:111]
	ds_read_b128 v[164:167], v196 offset:8192
	ds_read_b128 v[180:183], v196 offset:10240
	v_mfma_f32_32x32x16_bf16 v[48:63], v[136:139], v[152:155], v[48:63]
	ds_read_b128 v[184:187], v196 offset:12288
	ds_read_b128 v[188:191], v196 offset:14336
	v_mfma_f32_32x32x16_bf16 v[32:47], v[136:139], v[156:159], v[32:47]
	v_mfma_f32_32x32x16_bf16 v[80:95], v[140:143], v[144:147], v[80:95]
	v_mfma_f32_32x32x16_bf16 v[64:79], v[140:143], v[148:151], v[64:79]
	v_mfma_f32_32x32x16_bf16 v[16:31], v[140:143], v[152:155], v[16:31]
	v_mfma_f32_32x32x16_bf16 v[0:15], v[140:143], v[156:159], v[0:15]
	s_add_i32 s29, s29, -1
	s_cmp_lg_u32 s29, 0
	s_cbranch_scc1 .Lop4_loop
	s_mul_i32 s40, s34, 0x6000
	s_add_i32 s40, s40, 32
	v_add_u32_e32 v135, s40, v134
	v_add_u32_e32 v168, s40, v133
	v_add_u32_e32 v194, v135, v131
	v_add_u32_e32 v195, v168, v131
	s_waitcnt vmcnt(6)
	s_waitcnt lgkmcnt(0)
	s_barrier
; #define MFMA(a, b, c) __builtin_amdgcn_mfma_f32_32x32x16_bf16((a), (b), (c), 0, 0, 0)
; template <bool VMODE, int TJ>
; DI void gemm_mainloop(const bf16_t* __restrict__ W, const bf16_t* __restrict__ X, int NW, char* smem, f32x16 (&acc)[2][TJ]) {
;     ...
;         for (int ks = 0; ks < 32; ++ks) {
;             if (ks < 31) asm volatile("s_waitcnt vmcnt(6)" ::: "memory");
;             else asm volatile("s_waitcnt vmcnt(0)" ::: "memory");
;             __builtin_amdgcn_s_barrier();
;             const char* sw = smem + bc * STAGE + wf * 64 * 64;
;             const char* sx = smem + bc * STAGE + 8192 + wt * (32 * TJ) * 64;
;             bf16x8 fw[2], fx[TJ], gw[2], gx[TJ];
; #pragma unroll
;             for (int i = 0; i < 2; ++i) fw[i] = *(const bf16x8*)(sw + i * 32 * 64 + fo0);
; #pragma unroll
;             for (int j = 0; j < TJ; ++j) fx[j] = *(const bf16x8*)(sx + j * 32 * 64 + fo0);
;             __builtin_amdgcn_sched_barrier(0);
;             if (ks + 2 < 32) G_ISSUE(ks + 2, bn);
;             __builtin_amdgcn_sched_barrier(0);
; #pragma unroll
;             for (int i = 0; i < 2; ++i) gw[i] = *(const bf16x8*)(sw + i * 32 * 64 + fo1);
; #pragma unroll
;             for (int j = 0; j < TJ; ++j) gx[j] = *(const bf16x8*)(sx + j * 32 * 64 + fo1);
; #pragma unroll
;             for (int i = 0; i < 2; ++i)
; #pragma unroll
;                 for (int j = 0; j < TJ; ++j) acc[i][j] = VMODE ? MFMA(fx[j], fw[i], acc[i][j]) : MFMA(fw[i], fx[j], acc[i][j]);
; #pragma unroll
;             for (int i = 0; i < 2; ++i)
; #pragma unroll
;                 for (int j = 0; j < TJ; ++j) acc[i][j] = VMODE ? MFMA(gx[j], gw[i], acc[i][j]) : MFMA(gw[i], gx[j], acc[i][j]);
;             bc = (bc == 2) ? 0 : bc + 1; bn = (bn == 2) ? 0 : bn + 1;
;         }
;     }
;     ...
;     __syncthreads();
; template <int TJ>
; DI void outproj_tile(const Params& p, int l, char* smem, int b, int trow0, int n0) {
;     ...
;     const float* gt = p.mod + ((size_t)l * 9 + (trow0 < SEQ ? b : 8)) * 3072 + 2048 + n0 + 64 * wf;
;     const float* xs = src_row(p, l, b, trow0 + 32 * TJ * wt) + n0 + 64 * wf;
;     float* xd = dst_row(p, b, trow0 + 32 * TJ * wt) + n0 + 64 * wf;
	ds_read_b128 v[136:139], v194
	ds_read_b128 v[140:143], v194 offset:2048
	ds_read_b128 v[144:147], v195 offset:8192
	ds_read_b128 v[148:151], v195 offset:10240
	ds_read_b128 v[152:155], v195 offset:12288
	ds_read_b128 v[156:159], v195 offset:14336
	s_add_i32 s40, s34, 1
	s_cmp_lg_u32 s34, 2
	s_cselect_b32 s34, s40, 0
	s_add_i32 s40, s35, 1
	s_cmp_lg_u32 s35, 2
	s_cselect_b32 s35, s40, 0
	v_add_u32_e32 v169, v135, v132
	v_add_u32_e32 v196, v168, v132
	v_mfma_f32_32x32x16_bf16 v[112:127], v[160:163], v[164:167], v[112:127]
	v_mfma_f32_32x32x16_bf16 v[96:111], v[160:163], v[180:183], v[96:111]
	v_mfma_f32_32x32x16_bf16 v[48:63], v[160:163], v[184:187], v[48:63]
	v_mfma_f32_32x32x16_bf16 v[32:47], v[160:163], v[188:191], v[32:47]
	v_mfma_f32_32x32x16_bf16 v[80:95], v[176:179], v[164:167], v[80:95]
	v_mfma_f32_32x32x16_bf16 v[64:79], v[176:179], v[180:183], v[64:79]
	v_mfma_f32_32x32x16_bf16 v[16:31], v[176:179], v[184:187], v[16:31]
	v_mfma_f32_32x32x16_bf16 v[0:15], v[176:179], v[188:191], v[0:15]
	s_waitcnt lgkmcnt(0)
	v_mfma_f32_32x32x16_bf16 v[112:127], v[136:139], v[144:147], v[112:127]
	ds_read_b128 v[160:163], v169
	ds_read_b128 v[176:179], v169 offset:2048
	v_mfma_f32_32x32x16_bf16 v[96:111], v[136:139], v[148:151], v[96:111]
	ds_read_b128 v[164:167], v196 offset:8192
	ds_read_b128 v[180:183], v196 offset:10240
	v_mfma_f32_32x32x16_bf16 v[48:63], v[136:139], v[152:155], v[48:63]
	ds_read_b128 v[184:187], v196 offset:12288
	ds_read_b128 v[188:191], v196 offset:14336
	v_mfma_f32_32x32x16_bf16 v[32:47], v[136:139], v[156:159], v[32:47]
	v_mfma_f32_32x32x16_bf16 v[80:95], v[140:143], v[144:147], v[80:95]
	v_mfma_f32_32x32x16_bf16 v[64:79], v[140:143], v[148:151], v[64:79]
	v_mfma_f32_32x32x16_bf16 v[16:31], v[140:143], v[152:155], v[16:31]
	v_mfma_f32_32x32x16_bf16 v[0:15], v[140:143], v[156:159], v[0:15]
	s_mul_i32 s40, s34, 0x6000
	s_add_i32 s40, s40, 32
	v_add_u32_e32 v135, s40, v134
	v_add_u32_e32 v168, s40, v133
	v_add_u32_e32 v194, v135, v131
	v_add_u32_e32 v195, v168, v131
	s_waitcnt vmcnt(0)
	s_waitcnt lgkmcnt(0)
	s_barrier
	ds_read_b128 v[136:139], v194
	ds_read_b128 v[140:143], v194 offset:2048
	ds_read_b128 v[144:147], v195 offset:8192
	ds_read_b128 v[148:151], v195 offset:10240
	ds_read_b128 v[152:155], v195 offset:12288
	ds_read_b128 v[156:159], v195 offset:14336
	s_add_i32 s40, s34, 1
	s_cmp_lg_u32 s34, 2
	s_cselect_b32 s34, s40, 0
	s_add_i32 s40, s35, 1
	s_cmp_lg_u32 s35, 2
	s_cselect_b32 s35, s40, 0
	v_add_u32_e32 v169, v135, v132
	v_add_u32_e32 v196, v168, v132
	v_mfma_f32_32x32x16_bf16 v[112:127], v[160:163], v[164:167], v[112:127]
	v_mfma_f32_32x32x16_bf16 v[96:111], v[160:163], v[180:183], v[96:111]
	v_mfma_f32_32x32x16_bf16 v[48:63], v[160:163], v[184:187], v[48:63]
	v_mfma_f32_32x32x16_bf16 v[32:47], v[160:163], v[188:191], v[32:47]
	v_mfma_f32_32x32x16_bf16 v[80:95], v[176:179], v[164:167], v[80:95]
	v_mfma_f32_32x32x16_bf16 v[64:79], v[176:179], v[180:183], v[64:79]
	v_mfma_f32_32x32x16_bf16 v[16:31], v[176:179], v[184:187], v[16:31]
	v_mfma_f32_32x32x16_bf16 v[0:15], v[176:179], v[188:191], v[0:15]
	s_waitcnt lgkmcnt(0)
	v_mfma_f32_32x32x16_bf16 v[112:127], v[136:139], v[144:147], v[112:127]
	ds_read_b128 v[160:163], v169
	ds_read_b128 v[176:179], v169 offset:2048
	v_mfma_f32_32x32x16_bf16 v[96:111], v[136:139], v[148:151], v[96:111]
	ds_read_b128 v[164:167], v196 offset:8192
	ds_read_b128 v[180:183], v196 offset:10240
	v_mfma_f32_32x32x16_bf16 v[48:63], v[136:139], v[152:155], v[48:63]
	ds_read_b128 v[184:187], v196 offset:12288
	ds_read_b128 v[188:191], v196 offset:14336
	v_mfma_f32_32x32x16_bf16 v[32:47], v[136:139], v[156:159], v[32:47]
	v_mfma_f32_32x32x16_bf16 v[80:95], v[140:143], v[144:147], v[80:95]
	v_mfma_f32_32x32x16_bf16 v[64:79], v[140:143], v[148:151], v[64:79]
	v_mfma_f32_32x32x16_bf16 v[16:31], v[140:143], v[152:155], v[16:31]
	v_mfma_f32_32x32x16_bf16 v[0:15], v[140:143], v[156:159], v[0:15]
	s_waitcnt lgkmcnt(0)
	v_mfma_f32_32x32x16_bf16 v[112:127], v[160:163], v[164:167], v[112:127]
	v_mfma_f32_32x32x16_bf16 v[96:111], v[160:163], v[180:183], v[96:111]
	v_mfma_f32_32x32x16_bf16 v[48:63], v[160:163], v[184:187], v[48:63]
	v_mfma_f32_32x32x16_bf16 v[32:47], v[160:163], v[188:191], v[32:47]
	v_mfma_f32_32x32x16_bf16 v[80:95], v[176:179], v[164:167], v[80:95]
	v_mfma_f32_32x32x16_bf16 v[64:79], v[176:179], v[180:183], v[64:79]
	v_mfma_f32_32x32x16_bf16 v[16:31], v[176:179], v[184:187], v[16:31]
	v_mfma_f32_32x32x16_bf16 v[0:15], v[176:179], v[188:191], v[0:15]
	s_waitcnt vmcnt(0) lgkmcnt(0)
	s_barrier
	s_nop 7
	s_nop 7
	v_mov_b32_e32 v172, v64
	v_mov_b32_e32 v173, v65
	v_mov_b32_e32 v174, v66
	v_mov_b32_e32 v175, v67
	v_mov_b32_e32 v176, v68
	v_mov_b32_e32 v177, v69
	v_mov_b32_e32 v178, v70
	v_mov_b32_e32 v179, v71
	v_mov_b32_e32 v180, v72
	v_mov_b32_e32 v181, v73
	v_mov_b32_e32 v182, v74
	v_mov_b32_e32 v183, v75
	v_mov_b32_e32 v184, v76
	v_mov_b32_e32 v185, v77
	v_mov_b32_e32 v186, v78
	v_mov_b32_e32 v187, v79
	v_mov_b32_e32 v188, v80
	v_mov_b32_e32 v189, v81
	v_mov_b32_e32 v190, v82
	v_mov_b32_e32 v191, v83
	v_mov_b32_e32 v194, v84
	v_mov_b32_e32 v195, v85
	v_mov_b32_e32 v196, v86
	v_mov_b32_e32 v197, v87
	v_mov_b32_e32 v198, v88
	v_mov_b32_e32 v199, v89
	v_mov_b32_e32 v214, v90
	v_mov_b32_e32 v215, v91
	v_mov_b32_e32 v216, v92
	v_mov_b32_e32 v217, v93
	v_mov_b32_e32 v218, v94
	v_mov_b32_e32 v219, v95
	v_mov_b32_e32 v220, v96
	v_mov_b32_e32 v221, v97
	v_mov_b32_e32 v222, v98
	v_mov_b32_e32 v223, v99
	v_mov_b32_e32 v224, v100
	v_mov_b32_e32 v225, v101
	v_mov_b32_e32 v226, v102
	v_mov_b32_e32 v227, v103
	v_mov_b32_e32 v228, v104
	v_mov_b32_e32 v229, v105
	v_mov_b32_e32 v230, v106
	v_mov_b32_e32 v231, v107
	v_mov_b32_e32 v232, v108
	v_mov_b32_e32 v233, v109
	v_mov_b32_e32 v234, v110
	v_mov_b32_e32 v235, v111
	v_mov_b32_e32 v236, v112
	v_mov_b32_e32 v237, v113
	v_mov_b32_e32 v238, v114
	v_mov_b32_e32 v239, v115
	v_mov_b32_e32 v240, v116
	v_mov_b32_e32 v241, v117
	v_mov_b32_e32 v242, v118
	v_mov_b32_e32 v243, v119
	v_mov_b32_e32 v244, v120
	v_mov_b32_e32 v245, v121
	v_mov_b32_e32 v246, v122
	v_mov_b32_e32 v247, v123
	v_mov_b32_e32 v248, v124
	v_mov_b32_e32 v249, v125
	v_mov_b32_e32 v250, v126
	v_mov_b32_e32 v251, v127
	v_mov_b32_e32 v116, v200
	s_mov_b64 s[4:5], -1
	s_and_b64 vcc, exec, s[50:51]
	s_load_dwordx2 s[52:53], s[0:1], 0xe0
	v_ashrrev_i32_e32 v64, 1, v116
	v_and_b32_e32 v64, 0xffffffc0, v64
	v_add_u32_e32 v66, s28, v64
	v_cmp_gt_i32_e64 s[40:41], s61, v66
	v_cmp_lt_i32_e64 s[42:43], s21, v66
	s_branch .Lop4_epi

; #define MFMA(a, b, c) __builtin_amdgcn_mfma_f32_32x32x16_bf16((a), (b), (c), 0, 0, 0)
; #define G_ISSUE(ks_, buf_) do { \
;     const bf16_t* wq_ = wp + (ks_) * wks; const bf16_t* xq_ = xp + (ks_) * xks; char* lb_ = ld + (buf_) * STAGE; \
;     dma16(wq_, lb_); dma16(wq_ + 2048, lb_ + 4096); \
;     _Pragma("unroll") for (int i_ = 0; i_ < TJ; ++i_) dma16(xq_ + i_ * 2048, lb_ + 8192 + i_ * 4096); } while (0)
; template <bool VMODE, int TJ>
; DI void gemm_mainloop(const bf16_t* __restrict__ W, const bf16_t* __restrict__ X, int NW, char* smem, f32x16 (&acc)[2][TJ]) {
;     ...
;         for (int ks = 0; ks < 32; ++ks) {
;             if (ks < 31) asm volatile("s_waitcnt vmcnt(6)" ::: "memory");
;             else asm volatile("s_waitcnt vmcnt(0)" ::: "memory");
;             __builtin_amdgcn_s_barrier();
;             const char* sw = smem + bc * STAGE + wf * 64 * 64;
;             const char* sx = smem + bc * STAGE + 8192 + wt * (32 * TJ) * 64;
;             bf16x8 fw[2], fx[TJ], gw[2], gx[TJ];
; #pragma unroll
;             for (int i = 0; i < 2; ++i) fw[i] = *(const bf16x8*)(sw + i * 32 * 64 + fo0);
; #pragma unroll
;             for (int j = 0; j < TJ; ++j) fx[j] = *(const bf16x8*)(sx + j * 32 * 64 + fo0);
;             __builtin_amdgcn_sched_barrier(0);
;             if (ks + 2 < 32) G_ISSUE(ks + 2, bn);
;             __builtin_amdgcn_sched_barrier(0);
; #pragma unroll
;             for (int i = 0; i < 2; ++i) gw[i] = *(const bf16x8*)(sw + i * 32 * 64 + fo1);
; #pragma unroll
;             for (int j = 0; j < TJ; ++j) gx[j] = *(const bf16x8*)(sx + j * 32 * 64 + fo1);
; #pragma unroll
;             for (int i = 0; i < 2; ++i)
; #pragma unroll
;                 for (int j = 0; j < TJ; ++j) acc[i][j] = VMODE ? MFMA(fx[j], fw[i], acc[i][j]) : MFMA(fw[i], fx[j], acc[i][j]);
; #pragma unroll
;             for (int i = 0; i < 2; ++i)
; #pragma unroll
;                 for (int j = 0; j < TJ; ++j) acc[i][j] = VMODE ? MFMA(gx[j], gw[i], acc[i][j]) : MFMA(gw[i], gx[j], acc[i][j]);
.LBB0_202:
	s_waitcnt vmcnt(6)
	s_waitcnt lgkmcnt(0)
	s_barrier
	ds_read_b128 v[136:139], v242
	ds_read_b128 v[140:143], v242 offset:2048
	ds_read_b128 v[144:147], v243 offset:8192
	ds_read_b128 v[148:151], v243 offset:10240
	ds_read_b128 v[152:155], v243 offset:12288
	ds_read_b128 v[156:159], v243 offset:14336
	s_mul_i32 s29, s8, 0x6000
	s_add_i32 s101, s29, s100
	s_add_i32 s29, s28, 1
	s_cmp_lg_u32 s28, 2
	s_cselect_b32 s28, s29, 0
	s_add_i32 s29, s8, 1
	s_cmp_lg_u32 s8, 2
	s_cselect_b32 s8, s29, 0
	s_add_i32 s9, s9, -1
	s_add_u32 s6, s6, 0x120000
	s_addc_u32 s7, s7, 0
	s_add_u32 s4, s4, 0x38000
	s_addc_u32 s5, s5, 0
	s_mov_b32 m0, s101
	v_mfma_f32_32x32x16_bf16 v[112:127], v[160:163], v[164:167], v[112:127]
	global_load_lds_dwordx4 v170, s[4:5]
	s_add_u32 m0, s101, 0x1000
	v_mfma_f32_32x32x16_bf16 v[80:95], v[160:163], v[180:183], v[80:95]
	global_load_lds_dwordx4 v171, s[4:5]
	s_add_u32 m0, s101, 0x2000
	v_mfma_f32_32x32x16_bf16 v[48:63], v[160:163], v[184:187], v[48:63]
	global_load_lds_dwordx4 v172, s[6:7]
	s_add_u32 m0, s101, 0x3000
	v_mfma_f32_32x32x16_bf16 v[16:31], v[160:163], v[188:191], v[16:31]
	global_load_lds_dwordx4 v173, s[6:7]
	s_add_u32 m0, s101, 0x4000
	v_mfma_f32_32x32x16_bf16 v[96:111], v[176:179], v[164:167], v[96:111]
	global_load_lds_dwordx4 v174, s[6:7]
	s_add_u32 m0, s101, 0x5000
	v_mfma_f32_32x32x16_bf16 v[64:79], v[176:179], v[180:183], v[64:79]
	global_load_lds_dwordx4 v175, s[6:7]
	v_mfma_f32_32x32x16_bf16 v[32:47], v[176:179], v[184:187], v[32:47]
	v_mfma_f32_32x32x16_bf16 v[0:15], v[176:179], v[188:191], v[0:15]
	s_waitcnt lgkmcnt(0)
	v_mfma_f32_32x32x16_bf16 v[112:127], v[136:139], v[144:147], v[112:127]
	ds_read_b128 v[160:163], v244
	ds_read_b128 v[164:167], v245 offset:8192
	v_mfma_f32_32x32x16_bf16 v[80:95], v[136:139], v[148:151], v[80:95]
	ds_read_b128 v[176:179], v244 offset:2048
	ds_read_b128 v[180:183], v245 offset:10240
	v_mfma_f32_32x32x16_bf16 v[48:63], v[136:139], v[152:155], v[48:63]
	ds_read_b128 v[184:187], v245 offset:12288
	ds_read_b128 v[188:191], v245 offset:14336
	v_mfma_f32_32x32x16_bf16 v[16:31], v[136:139], v[156:159], v[16:31]
	v_mfma_f32_32x32x16_bf16 v[96:111], v[140:143], v[144:147], v[96:111]
	v_mfma_f32_32x32x16_bf16 v[64:79], v[140:143], v[148:151], v[64:79]
	v_mfma_f32_32x32x16_bf16 v[32:47], v[140:143], v[152:155], v[32:47]
	v_mfma_f32_32x32x16_bf16 v[0:15], v[140:143], v[156:159], v[0:15]
	s_cmp_lg_u32 s9, 0
	s_cbranch_scc0 .Lip3_exit_a
	s_waitcnt vmcnt(6)
	s_waitcnt lgkmcnt(0)
	s_barrier
; #define MFMA(a, b, c) __builtin_amdgcn_mfma_f32_32x32x16_bf16((a), (b), (c), 0, 0, 0)
; #define G_ISSUE(ks_, buf_) do { \
;     const bf16_t* wq_ = wp + (ks_) * wks; const bf16_t* xq_ = xp + (ks_) * xks; char* lb_ = ld + (buf_) * STAGE; \
;     dma16(wq_, lb_); dma16(wq_ + 2048, lb_ + 4096); \
;     _Pragma("unroll") for (int i_ = 0; i_ < TJ; ++i_) dma16(xq_ + i_ * 2048, lb_ + 8192 + i_ * 4096); } while (0)
; template <bool VMODE, int TJ>
; DI void gemm_mainloop(const bf16_t* __restrict__ W, const bf16_t* __restrict__ X, int NW, char* smem, f32x16 (&acc)[2][TJ]) {
;     ...
;         for (int ks = 0; ks < 32; ++ks) {
;             if (ks < 31) asm volatile("s_waitcnt vmcnt(6)" ::: "memory");
;             else asm volatile("s_waitcnt vmcnt(0)" ::: "memory");
;             __builtin_amdgcn_s_barrier();
;             const char* sw = smem + bc * STAGE + wf * 64 * 64;
;             const char* sx = smem + bc * STAGE + 8192 + wt * (32 * TJ) * 64;
;             bf16x8 fw[2], fx[TJ], gw[2], gx[TJ];
; #pragma unroll
;             for (int i = 0; i < 2; ++i) fw[i] = *(const bf16x8*)(sw + i * 32 * 64 + fo0);
; #pragma unroll
;             for (int j = 0; j < TJ; ++j) fx[j] = *(const bf16x8*)(sx + j * 32 * 64 + fo0);
;             __builtin_amdgcn_sched_barrier(0);
;             if (ks + 2 < 32) G_ISSUE(ks + 2, bn);
;             __builtin_amdgcn_sched_barrier(0);
; #pragma unroll
;             for (int i = 0; i < 2; ++i) gw[i] = *(const bf16x8*)(sw + i * 32 * 64 + fo1);
; #pragma unroll
;             for (int j = 0; j < TJ; ++j) gx[j] = *(const bf16x8*)(sx + j * 32 * 64 + fo1);
; #pragma unroll
;             for (int i = 0; i < 2; ++i)
; #pragma unroll
;                 for (int j = 0; j < TJ; ++j) acc[i][j] = VMODE ? MFMA(fx[j], fw[i], acc[i][j]) : MFMA(fw[i], fx[j], acc[i][j]);
; #pragma unroll
;             for (int i = 0; i < 2; ++i)
; #pragma unroll
;                 for (int j = 0; j < TJ; ++j) acc[i][j] = VMODE ? MFMA(gx[j], gw[i], acc[i][j]) : MFMA(gw[i], gx[j], acc[i][j]);
	ds_read_b128 v[136:139], v246
	ds_read_b128 v[140:143], v246 offset:2048
	ds_read_b128 v[144:147], v247 offset:8192
	ds_read_b128 v[148:151], v247 offset:10240
	ds_read_b128 v[152:155], v247 offset:12288
	ds_read_b128 v[156:159], v247 offset:14336
	s_mul_i32 s29, s8, 0x6000
	s_add_i32 s101, s29, s100
	s_add_i32 s29, s28, 1
	s_cmp_lg_u32 s28, 2
	s_cselect_b32 s28, s29, 0
	s_add_i32 s29, s8, 1
	s_cmp_lg_u32 s8, 2
	s_cselect_b32 s8, s29, 0
	s_add_i32 s9, s9, -1
	s_add_u32 s6, s6, 0x120000
	s_addc_u32 s7, s7, 0
	s_add_u32 s4, s4, 0x38000
	s_addc_u32 s5, s5, 0
	s_mov_b32 m0, s101
	v_mfma_f32_32x32x16_bf16 v[112:127], v[160:163], v[164:167], v[112:127]
	global_load_lds_dwordx4 v170, s[4:5]
	s_add_u32 m0, s101, 0x1000
	v_mfma_f32_32x32x16_bf16 v[80:95], v[160:163], v[180:183], v[80:95]
	global_load_lds_dwordx4 v171, s[4:5]
	s_add_u32 m0, s101, 0x2000
	v_mfma_f32_32x32x16_bf16 v[48:63], v[160:163], v[184:187], v[48:63]
	global_load_lds_dwordx4 v172, s[6:7]
	s_add_u32 m0, s101, 0x3000
	v_mfma_f32_32x32x16_bf16 v[16:31], v[160:163], v[188:191], v[16:31]
	global_load_lds_dwordx4 v173, s[6:7]
	s_add_u32 m0, s101, 0x4000
	v_mfma_f32_32x32x16_bf16 v[96:111], v[176:179], v[164:167], v[96:111]
	global_load_lds_dwordx4 v174, s[6:7]
	s_add_u32 m0, s101, 0x5000
	v_mfma_f32_32x32x16_bf16 v[64:79], v[176:179], v[180:183], v[64:79]
	global_load_lds_dwordx4 v175, s[6:7]
	v_mfma_f32_32x32x16_bf16 v[32:47], v[176:179], v[184:187], v[32:47]
	v_mfma_f32_32x32x16_bf16 v[0:15], v[176:179], v[188:191], v[0:15]
	s_waitcnt lgkmcnt(0)
	v_mfma_f32_32x32x16_bf16 v[112:127], v[136:139], v[144:147], v[112:127]
	ds_read_b128 v[160:163], v248
	ds_read_b128 v[164:167], v249 offset:8192
	v_mfma_f32_32x32x16_bf16 v[80:95], v[136:139], v[148:151], v[80:95]
	ds_read_b128 v[176:179], v248 offset:2048
	ds_read_b128 v[180:183], v249 offset:10240
	v_mfma_f32_32x32x16_bf16 v[48:63], v[136:139], v[152:155], v[48:63]
	ds_read_b128 v[184:187], v249 offset:12288
	ds_read_b128 v[188:191], v249 offset:14336
	v_mfma_f32_32x32x16_bf16 v[16:31], v[136:139], v[156:159], v[16:31]
	v_mfma_f32_32x32x16_bf16 v[96:111], v[140:143], v[144:147], v[96:111]
	v_mfma_f32_32x32x16_bf16 v[64:79], v[140:143], v[148:151], v[64:79]
	v_mfma_f32_32x32x16_bf16 v[32:47], v[140:143], v[152:155], v[32:47]
	v_mfma_f32_32x32x16_bf16 v[0:15], v[140:143], v[156:159], v[0:15]
	s_cmp_lg_u32 s9, 0
	s_cbranch_scc0 .Lip3_exit_a
	s_waitcnt vmcnt(6)
	s_waitcnt lgkmcnt(0)
	s_barrier
	ds_read_b128 v[136:139], v238
	ds_read_b128 v[140:143], v238 offset:2048
	ds_read_b128 v[144:147], v239 offset:8192
	ds_read_b128 v[148:151], v239 offset:10240
	ds_read_b128 v[152:155], v239 offset:12288
	ds_read_b128 v[156:159], v239 offset:14336
	s_mul_i32 s29, s8, 0x6000
	s_add_i32 s101, s29, s100
	s_add_i32 s29, s28, 1
	s_cmp_lg_u32 s28, 2
	s_cselect_b32 s28, s29, 0
	s_add_i32 s29, s8, 1
	s_cmp_lg_u32 s8, 2
	s_cselect_b32 s8, s29, 0
	s_add_i32 s9, s9, -1
	s_add_u32 s6, s6, 0x120000
	s_addc_u32 s7, s7, 0
	s_add_u32 s4, s4, 0x38000
	s_addc_u32 s5, s5, 0
	s_mov_b32 m0, s101
	v_mfma_f32_32x32x16_bf16 v[112:127], v[160:163], v[164:167], v[112:127]
	global_load_lds_dwordx4 v170, s[4:5]
	s_add_u32 m0, s101, 0x1000
	v_mfma_f32_32x32x16_bf16 v[80:95], v[160:163], v[180:183], v[80:95]
	global_load_lds_dwordx4 v171, s[4:5]
	s_add_u32 m0, s101, 0x2000
	v_mfma_f32_32x32x16_bf16 v[48:63], v[160:163], v[184:187], v[48:63]
	global_load_lds_dwordx4 v172, s[6:7]
	s_add_u32 m0, s101, 0x3000
	v_mfma_f32_32x32x16_bf16 v[16:31], v[160:163], v[188:191], v[16:31]
	global_load_lds_dwordx4 v173, s[6:7]
	s_add_u32 m0, s101, 0x4000
	v_mfma_f32_32x32x16_bf16 v[96:111], v[176:179], v[164:167], v[96:111]
	global_load_lds_dwordx4 v174, s[6:7]
	s_add_u32 m0, s101, 0x5000
	v_mfma_f32_32x32x16_bf16 v[64:79], v[176:179], v[180:183], v[64:79]
	global_load_lds_dwordx4 v175, s[6:7]
	v_mfma_f32_32x32x16_bf16 v[32:47], v[176:179], v[184:187], v[32:47]
	v_mfma_f32_32x32x16_bf16 v[0:15], v[176:179], v[188:191], v[0:15]
	s_waitcnt lgkmcnt(0)
	v_mfma_f32_32x32x16_bf16 v[112:127], v[136:139], v[144:147], v[112:127]
	ds_read_b128 v[160:163], v240
	ds_read_b128 v[164:167], v241 offset:8192
	v_mfma_f32_32x32x16_bf16 v[80:95], v[136:139], v[148:151], v[80:95]
	ds_read_b128 v[176:179], v240 offset:2048
	ds_read_b128 v[180:183], v241 offset:10240
	v_mfma_f32_32x32x16_bf16 v[48:63], v[136:139], v[152:155], v[48:63]
	ds_read_b128 v[184:187], v241 offset:12288
	ds_read_b128 v[188:191], v241 offset:14336
	v_mfma_f32_32x32x16_bf16 v[16:31], v[136:139], v[156:159], v[16:31]
	v_mfma_f32_32x32x16_bf16 v[96:111], v[140:143], v[144:147], v[96:111]
	v_mfma_f32_32x32x16_bf16 v[64:79], v[140:143], v[148:151], v[64:79]
	v_mfma_f32_32x32x16_bf16 v[32:47], v[140:143], v[152:155], v[32:47]
	v_mfma_f32_32x32x16_bf16 v[0:15], v[140:143], v[156:159], v[0:15]
	s_cmp_lg_u32 s9, 0
	s_cbranch_scc1 .LBB0_202

; #define MFMA(a, b, c) __builtin_amdgcn_mfma_f32_32x32x16_bf16((a), (b), (c), 0, 0, 0)
; #define G_ISSUE(ks_, buf_) do { \
;     const bf16_t* wq_ = wp + (ks_) * wks; const bf16_t* xq_ = xp + (ks_) * xks; char* lb_ = ld + (buf_) * STAGE; \
;     dma16(wq_, lb_); dma16(wq_ + 2048, lb_ + 4096); \
;     _Pragma("unroll") for (int i_ = 0; i_ < TJ; ++i_) dma16(xq_ + i_ * 2048, lb_ + 8192 + i_ * 4096); } while (0)
; template <bool VMODE, int TJ>
; DI void gemm_mainloop(const bf16_t* __restrict__ W, const bf16_t* __restrict__ X, int NW, char* smem, f32x16 (&acc)[2][TJ]) {
;     ...
;         for (int ks = 0; ks < 32; ++ks) {
;             if (ks < 31) asm volatile("s_waitcnt vmcnt(6)" ::: "memory");
;             else asm volatile("s_waitcnt vmcnt(0)" ::: "memory");
;             __builtin_amdgcn_s_barrier();
;             const char* sw = smem + bc * STAGE + wf * 64 * 64;
;             const char* sx = smem + bc * STAGE + 8192 + wt * (32 * TJ) * 64;
;             bf16x8 fw[2], fx[TJ], gw[2], gx[TJ];
; #pragma unroll
;             for (int i = 0; i < 2; ++i) fw[i] = *(const bf16x8*)(sw + i * 32 * 64 + fo0);
; #pragma unroll
;             for (int j = 0; j < TJ; ++j) fx[j] = *(const bf16x8*)(sx + j * 32 * 64 + fo0);
;             __builtin_amdgcn_sched_barrier(0);
;             if (ks + 2 < 32) G_ISSUE(ks + 2, bn);
;             __builtin_amdgcn_sched_barrier(0);
; #pragma unroll
;             for (int i = 0; i < 2; ++i) gw[i] = *(const bf16x8*)(sw + i * 32 * 64 + fo1);
; #pragma unroll
;             for (int j = 0; j < TJ; ++j) gx[j] = *(const bf16x8*)(sx + j * 32 * 64 + fo1);
; #pragma unroll
;             for (int i = 0; i < 2; ++i)
; #pragma unroll
;                 for (int j = 0; j < TJ; ++j) acc[i][j] = VMODE ? MFMA(fx[j], fw[i], acc[i][j]) : MFMA(fw[i], fx[j], acc[i][j]);
; #pragma unroll
;             for (int i = 0; i < 2; ++i)
; #pragma unroll
;                 for (int j = 0; j < TJ; ++j) acc[i][j] = VMODE ? MFMA(gx[j], gw[i], acc[i][j]) : MFMA(gw[i], gx[j], acc[i][j]);
.LBB0_289:
	s_waitcnt vmcnt(6)
	s_waitcnt lgkmcnt(0)
	s_barrier
	ds_read_b128 v[136:139], v242
	ds_read_b128 v[140:143], v242 offset:2048
	ds_read_b128 v[144:147], v243 offset:8192
	ds_read_b128 v[148:151], v243 offset:10240
	ds_read_b128 v[152:155], v243 offset:12288
	ds_read_b128 v[156:159], v243 offset:14336
	s_mul_i32 s7, s4, 0x6000
	s_add_i32 s101, s7, s100
	s_add_i32 s7, s6, 1
	s_cmp_lg_u32 s6, 2
	s_cselect_b32 s6, s7, 0
	s_add_i32 s7, s4, 1
	s_cmp_lg_u32 s4, 2
	s_cselect_b32 s4, s7, 0
	s_add_i32 s5, s5, -1
	s_add_u32 s56, s56, 0x120000
	s_addc_u32 s57, s57, 0
	s_add_u32 s52, s52, 0x38000
	s_addc_u32 s53, s53, 0
	s_mov_b32 m0, s101
	v_mfma_f32_32x32x16_bf16 v[112:127], v[160:163], v[164:167], v[112:127]
	global_load_lds_dwordx4 v170, s[52:53]
	s_add_u32 m0, s101, 0x1000
	v_mfma_f32_32x32x16_bf16 v[96:111], v[180:183], v[164:167], v[96:111]
	global_load_lds_dwordx4 v171, s[52:53]
	s_add_u32 m0, s101, 0x2000
	v_mfma_f32_32x32x16_bf16 v[80:95], v[184:187], v[164:167], v[80:95]
	global_load_lds_dwordx4 v172, s[56:57]
	s_add_u32 m0, s101, 0x3000
	v_mfma_f32_32x32x16_bf16 v[64:79], v[188:191], v[164:167], v[64:79]
	global_load_lds_dwordx4 v173, s[56:57]
	s_add_u32 m0, s101, 0x4000
	v_mfma_f32_32x32x16_bf16 v[48:63], v[160:163], v[176:179], v[48:63]
	global_load_lds_dwordx4 v174, s[56:57]
	s_add_u32 m0, s101, 0x5000
	v_mfma_f32_32x32x16_bf16 v[32:47], v[180:183], v[176:179], v[32:47]
	global_load_lds_dwordx4 v175, s[56:57]
	v_mfma_f32_32x32x16_bf16 v[16:31], v[184:187], v[176:179], v[16:31]
	v_mfma_f32_32x32x16_bf16 v[0:15], v[188:191], v[176:179], v[0:15]
	s_waitcnt lgkmcnt(0)
	v_mfma_f32_32x32x16_bf16 v[112:127], v[144:147], v[136:139], v[112:127]
	ds_read_b128 v[160:163], v245 offset:8192
	ds_read_b128 v[164:167], v244
	v_mfma_f32_32x32x16_bf16 v[96:111], v[148:151], v[136:139], v[96:111]
	ds_read_b128 v[176:179], v244 offset:2048
	ds_read_b128 v[180:183], v245 offset:10240
	v_mfma_f32_32x32x16_bf16 v[80:95], v[152:155], v[136:139], v[80:95]
	ds_read_b128 v[184:187], v245 offset:12288
	ds_read_b128 v[188:191], v245 offset:14336
	v_mfma_f32_32x32x16_bf16 v[64:79], v[156:159], v[136:139], v[64:79]
	v_mfma_f32_32x32x16_bf16 v[48:63], v[144:147], v[140:143], v[48:63]
	v_mfma_f32_32x32x16_bf16 v[32:47], v[148:151], v[140:143], v[32:47]
	v_mfma_f32_32x32x16_bf16 v[16:31], v[152:155], v[140:143], v[16:31]
	v_mfma_f32_32x32x16_bf16 v[0:15], v[156:159], v[140:143], v[0:15]
	s_cmp_lg_u32 s5, 0
	s_cbranch_scc0 .Lip3_exit_b
	s_waitcnt vmcnt(6)
	s_waitcnt lgkmcnt(0)
	s_barrier
; #define MFMA(a, b, c) __builtin_amdgcn_mfma_f32_32x32x16_bf16((a), (b), (c), 0, 0, 0)
; #define G_ISSUE(ks_, buf_) do { \
;     const bf16_t* wq_ = wp + (ks_) * wks; const bf16_t* xq_ = xp + (ks_) * xks; char* lb_ = ld + (buf_) * STAGE; \
;     dma16(wq_, lb_); dma16(wq_ + 2048, lb_ + 4096); \
;     _Pragma("unroll") for (int i_ = 0; i_ < TJ; ++i_) dma16(xq_ + i_ * 2048, lb_ + 8192 + i_ * 4096); } while (0)
; template <bool VMODE, int TJ>
; DI void gemm_mainloop(const bf16_t* __restrict__ W, const bf16_t* __restrict__ X, int NW, char* smem, f32x16 (&acc)[2][TJ]) {
;     ...
;         for (int ks = 0; ks < 32; ++ks) {
;             if (ks < 31) asm volatile("s_waitcnt vmcnt(6)" ::: "memory");
;             else asm volatile("s_waitcnt vmcnt(0)" ::: "memory");
;             __builtin_amdgcn_s_barrier();
;             const char* sw = smem + bc * STAGE + wf * 64 * 64;
;             const char* sx = smem + bc * STAGE + 8192 + wt * (32 * TJ) * 64;
;             bf16x8 fw[2], fx[TJ], gw[2], gx[TJ];
; #pragma unroll
;             for (int i = 0; i < 2; ++i) fw[i] = *(const bf16x8*)(sw + i * 32 * 64 + fo0);
; #pragma unroll
;             for (int j = 0; j < TJ; ++j) fx[j] = *(const bf16x8*)(sx + j * 32 * 64 + fo0);
;             __builtin_amdgcn_sched_barrier(0);
;             if (ks + 2 < 32) G_ISSUE(ks + 2, bn);
;             __builtin_amdgcn_sched_barrier(0);
; #pragma unroll
;             for (int i = 0; i < 2; ++i) gw[i] = *(const bf16x8*)(sw + i * 32 * 64 + fo1);
; #pragma unroll
;             for (int j = 0; j < TJ; ++j) gx[j] = *(const bf16x8*)(sx + j * 32 * 64 + fo1);
; #pragma unroll
;             for (int i = 0; i < 2; ++i)
; #pragma unroll
;                 for (int j = 0; j < TJ; ++j) acc[i][j] = VMODE ? MFMA(fx[j], fw[i], acc[i][j]) : MFMA(fw[i], fx[j], acc[i][j]);
; #pragma unroll
;             for (int i = 0; i < 2; ++i)
; #pragma unroll
;                 for (int j = 0; j < TJ; ++j) acc[i][j] = VMODE ? MFMA(gx[j], gw[i], acc[i][j]) : MFMA(gw[i], gx[j], acc[i][j]);
	ds_read_b128 v[136:139], v246
	ds_read_b128 v[140:143], v246 offset:2048
	ds_read_b128 v[144:147], v247 offset:8192
	ds_read_b128 v[148:151], v247 offset:10240
	ds_read_b128 v[152:155], v247 offset:12288
	ds_read_b128 v[156:159], v247 offset:14336
	s_mul_i32 s7, s4, 0x6000
	s_add_i32 s101, s7, s100
	s_add_i32 s7, s6, 1
	s_cmp_lg_u32 s6, 2
	s_cselect_b32 s6, s7, 0
	s_add_i32 s7, s4, 1
	s_cmp_lg_u32 s4, 2
	s_cselect_b32 s4, s7, 0
	s_add_i32 s5, s5, -1
	s_add_u32 s56, s56, 0x120000
	s_addc_u32 s57, s57, 0
	s_add_u32 s52, s52, 0x38000
	s_addc_u32 s53, s53, 0
	s_mov_b32 m0, s101
	v_mfma_f32_32x32x16_bf16 v[112:127], v[160:163], v[164:167], v[112:127]
	global_load_lds_dwordx4 v170, s[52:53]
	s_add_u32 m0, s101, 0x1000
	v_mfma_f32_32x32x16_bf16 v[96:111], v[180:183], v[164:167], v[96:111]
	global_load_lds_dwordx4 v171, s[52:53]
	s_add_u32 m0, s101, 0x2000
	v_mfma_f32_32x32x16_bf16 v[80:95], v[184:187], v[164:167], v[80:95]
	global_load_lds_dwordx4 v172, s[56:57]
	s_add_u32 m0, s101, 0x3000
	v_mfma_f32_32x32x16_bf16 v[64:79], v[188:191], v[164:167], v[64:79]
	global_load_lds_dwordx4 v173, s[56:57]
	s_add_u32 m0, s101, 0x4000
	v_mfma_f32_32x32x16_bf16 v[48:63], v[160:163], v[176:179], v[48:63]
	global_load_lds_dwordx4 v174, s[56:57]
	s_add_u32 m0, s101, 0x5000
	v_mfma_f32_32x32x16_bf16 v[32:47], v[180:183], v[176:179], v[32:47]
	global_load_lds_dwordx4 v175, s[56:57]
	v_mfma_f32_32x32x16_bf16 v[16:31], v[184:187], v[176:179], v[16:31]
	v_mfma_f32_32x32x16_bf16 v[0:15], v[188:191], v[176:179], v[0:15]
	s_waitcnt lgkmcnt(0)
	v_mfma_f32_32x32x16_bf16 v[112:127], v[144:147], v[136:139], v[112:127]
	ds_read_b128 v[160:163], v249 offset:8192
	ds_read_b128 v[164:167], v248
	v_mfma_f32_32x32x16_bf16 v[96:111], v[148:151], v[136:139], v[96:111]
	ds_read_b128 v[176:179], v248 offset:2048
	ds_read_b128 v[180:183], v249 offset:10240
	v_mfma_f32_32x32x16_bf16 v[80:95], v[152:155], v[136:139], v[80:95]
	ds_read_b128 v[184:187], v249 offset:12288
	ds_read_b128 v[188:191], v249 offset:14336
	v_mfma_f32_32x32x16_bf16 v[64:79], v[156:159], v[136:139], v[64:79]
	v_mfma_f32_32x32x16_bf16 v[48:63], v[144:147], v[140:143], v[48:63]
	v_mfma_f32_32x32x16_bf16 v[32:47], v[148:151], v[140:143], v[32:47]
	v_mfma_f32_32x32x16_bf16 v[16:31], v[152:155], v[140:143], v[16:31]
	v_mfma_f32_32x32x16_bf16 v[0:15], v[156:159], v[140:143], v[0:15]
	s_cmp_lg_u32 s5, 0
	s_cbranch_scc0 .Lip3_exit_b
	s_waitcnt vmcnt(6)
	s_waitcnt lgkmcnt(0)
	s_barrier
	ds_read_b128 v[136:139], v238
	ds_read_b128 v[140:143], v238 offset:2048
	ds_read_b128 v[144:147], v239 offset:8192
	ds_read_b128 v[148:151], v239 offset:10240
	ds_read_b128 v[152:155], v239 offset:12288
	ds_read_b128 v[156:159], v239 offset:14336
	s_mul_i32 s7, s4, 0x6000
	s_add_i32 s101, s7, s100
	s_add_i32 s7, s6, 1
	s_cmp_lg_u32 s6, 2
	s_cselect_b32 s6, s7, 0
	s_add_i32 s7, s4, 1
	s_cmp_lg_u32 s4, 2
	s_cselect_b32 s4, s7, 0
	s_add_i32 s5, s5, -1
	s_add_u32 s56, s56, 0x120000
	s_addc_u32 s57, s57, 0
	s_add_u32 s52, s52, 0x38000
	s_addc_u32 s53, s53, 0
	s_mov_b32 m0, s101
	v_mfma_f32_32x32x16_bf16 v[112:127], v[160:163], v[164:167], v[112:127]
	global_load_lds_dwordx4 v170, s[52:53]
	s_add_u32 m0, s101, 0x1000
	v_mfma_f32_32x32x16_bf16 v[96:111], v[180:183], v[164:167], v[96:111]
	global_load_lds_dwordx4 v171, s[52:53]
	s_add_u32 m0, s101, 0x2000
	v_mfma_f32_32x32x16_bf16 v[80:95], v[184:187], v[164:167], v[80:95]
	global_load_lds_dwordx4 v172, s[56:57]
	s_add_u32 m0, s101, 0x3000
	v_mfma_f32_32x32x16_bf16 v[64:79], v[188:191], v[164:167], v[64:79]
	global_load_lds_dwordx4 v173, s[56:57]
	s_add_u32 m0, s101, 0x4000
	v_mfma_f32_32x32x16_bf16 v[48:63], v[160:163], v[176:179], v[48:63]
	global_load_lds_dwordx4 v174, s[56:57]
	s_add_u32 m0, s101, 0x5000
	v_mfma_f32_32x32x16_bf16 v[32:47], v[180:183], v[176:179], v[32:47]
	global_load_lds_dwordx4 v175, s[56:57]
	v_mfma_f32_32x32x16_bf16 v[16:31], v[184:187], v[176:179], v[16:31]
	v_mfma_f32_32x32x16_bf16 v[0:15], v[188:191], v[176:179], v[0:15]
	s_waitcnt lgkmcnt(0)
	v_mfma_f32_32x32x16_bf16 v[112:127], v[144:147], v[136:139], v[112:127]
	ds_read_b128 v[160:163], v241 offset:8192
	ds_read_b128 v[164:167], v240
	v_mfma_f32_32x32x16_bf16 v[96:111], v[148:151], v[136:139], v[96:111]
	ds_read_b128 v[176:179], v240 offset:2048
	ds_read_b128 v[180:183], v241 offset:10240
	v_mfma_f32_32x32x16_bf16 v[80:95], v[152:155], v[136:139], v[80:95]
	ds_read_b128 v[184:187], v241 offset:12288
	ds_read_b128 v[188:191], v241 offset:14336
	v_mfma_f32_32x32x16_bf16 v[64:79], v[156:159], v[136:139], v[64:79]
	v_mfma_f32_32x32x16_bf16 v[48:63], v[144:147], v[140:143], v[48:63]
	v_mfma_f32_32x32x16_bf16 v[32:47], v[148:151], v[140:143], v[32:47]
	v_mfma_f32_32x32x16_bf16 v[16:31], v[152:155], v[140:143], v[16:31]
	v_mfma_f32_32x32x16_bf16 v[0:15], v[156:159], v[140:143], v[0:15]
	s_cmp_lg_u32 s5, 0
	s_cbranch_scc1 .LBB0_289
